# software-pipelined post loop: next iteration's 32 loads issued into a second register set before the current rows' compute
# speedup vs baseline: 1.0030x; 1.0030x over previous
; __device__ __forceinline__ float bf1(bf16 h) { return __uint_as_float(((unsigned)h) << 16); }
; __device__ __forceinline__ void phase_post(const Args& A, const Ctx& C0, int l, int nskip) {
;     ...
;     if (C.bid >= nskip)
;     for (int row0 = (C.bid - nskip) * 8; row0 < M; row0 += (C.G - nskip) * 8) {
;         float o[8], v[8], gr[8], rk[8];
; #pragma unroll
;         for (int i = 0; i < 8; ++i) { const size_t row = (size_t)(row0 + i);
;             o[i] = ((const float*)(Ub + row * UPITCH_B + UXC_B))[c]; v[i] = SCN[row * 3072 + hd * 384 + 320 + C.lane];
;             gr[i] = bf1(U[row * DIN + C_GR + c]); rk[i] = RKB[row * 8 + hd]; }
.LBB0_1183:
	v_readlane_b32 s0, v255, 53
	s_cmp_eq_u32 s0, 3
	s_mov_b64 s[40:41], 0
	s_cselect_b64 s[38:39], -1, 0
	s_cmp_lg_u32 s0, 3
	s_cbranch_scc1 .LBB0_1189
	v_mov_b32_e32 v2, v185
	v_readlane_b32 s0, v253, 3
	v_readlane_b32 s2, v253, 0
	v_readlane_b32 s40, v253, 4
	v_readlane_b32 s3, v253, 17
	v_readlane_b32 s41, v253, 5
	v_readfirstlane_b32 s1, v2
	s_cmp_lt_i32 s2, s3
	s_cbranch_scc1 .LBB0_1188
	v_readlane_b32 s3, v253, 17
	s_sub_i32 s2, s2, s3
	s_lshl_b32 s42, s2, 3
	s_cmpk_gt_u32 s42, 0x80ff
	s_cbranch_scc1 .LBB0_1188
	v_mov_b32_e32 v0, s1
	s_movk_i32 s2, 0xffc0
	v_bfi_b32 v6, s2, v0, v2
	v_readlane_b32 s2, v255, 42
	v_readlane_b32 s44, v255, 20
	v_readlane_b32 s56, v255, 32
	v_add_u32_e32 v4, s2, v6
	v_ashrrev_i32_e32 v5, 31, v4
	v_lshlrev_b64 v[4:5], 2, v[4:5]
	v_readlane_b32 s57, v255, 33
	v_readlane_b32 s58, v255, 34
	v_readlane_b32 s59, v255, 35
	v_lshl_add_u64 v[8:9], s[56:57], 0, v[4:5]
	global_load_dword v0, v[8:9], off
	v_lshl_add_u64 v[4:5], s[58:59], 0, v[4:5]
	global_load_dword v16, v[4:5], off
	s_ashr_i32 s2, s1, 6
	v_readlane_b32 s1, v253, 17
	s_sub_i32 s10, s0, s1
	v_readlane_b32 s3, v255, 43
	v_readlane_b32 s45, v255, 21
	v_ashrrev_i32_e32 v7, 31, v6
	s_lshl_b32 s44, s10, 3
	s_ashr_i32 s43, s42, 31
	v_readlane_b32 s46, v255, 22
	v_readlane_b32 s47, v255, 23
	s_mul_i32 s8, s2, 0x180
	s_ashr_i32 s3, s2, 31
	s_lshl_b64 s[0:1], s[42:43], 12
	v_lshlrev_b64 v[8:9], 1, v[6:7]
	s_ashr_i32 s45, s44, 31
	v_and_b32_e32 v4, 63, v2
	s_ashr_i32 s9, s8, 31
	s_waitcnt lgkmcnt(0)
	v_lshl_add_u64 v[2:3], s[0:1], 0, v[8:9]
	s_lshl_b64 s[46:47], s[44:45], 12
	s_lshl_b64 s[0:1], s[42:43], 5
	s_lshl_b64 s[2:3], s[2:3], 2
	v_readlane_b32 s50, v255, 26
	v_readlane_b32 s51, v255, 27
	s_add_u32 s2, s0, s2
	s_addc_u32 s3, s1, s3
	s_lshl_b64 s[50:51], s[44:45], 5
	s_mul_i32 s12, s42, 0x3000
	s_lshl_b64 s[0:1], s[8:9], 2
	s_mul_hi_i32 s11, s42, 0x3000
	s_add_u32 s0, s12, s0
	s_addc_u32 s1, s11, s1
	v_lshl_or_b32 v4, v4, 2, s0
	s_mul_i32 s0, s42, 0x2b00
	v_readlane_b32 s8, v254, 58
	v_mov_b32_e32 v5, s1
	s_mul_hi_i32 s1, s42, 0x2b00
	s_add_u32 s0, s8, s0
	v_readlane_b32 s8, v254, 59
	v_readlane_b32 s52, v255, 28
	v_readlane_b32 s53, v255, 29
	v_readlane_b32 s54, v255, 30
	v_readlane_b32 s55, v255, 31
	s_addc_u32 s1, s8, s1
	v_mov_b32_e32 v10, 0x2b00
	s_mul_i32 s52, s10, 0x18000
	s_mul_hi_i32 s53, s44, 0x3000
	v_lshl_add_u64 v[6:7], v[6:7], 2, s[0:1]
	s_mul_i32 s54, s10, 0x15800
	s_mul_hi_i32 s55, s44, 0x2b00
	v_mad_i64_i32 v[8:9], s[0:1], s42, v10, v[8:9]
	v_mov_b32_e32 v50, 0x3a27c5ac
	v_readlane_b32 s48, v255, 24
	v_readlane_b32 s49, v255, 25
	v_add_co_u32_e32 v52, vcc, 0xfffee000, v6
	s_add_u32 s0, s40, s2
	s_nop 0
	v_addc_co_u32_e32 v53, vcc, -1, v7, vcc
	global_load_dword v62, v[52:53], off offset:-3328
	v_lshl_add_u64 v[52:53], s[40:41], 0, v[4:5]
	v_add_co_u32_e32 v54, vcc, 0x256d7000, v52
	s_addc_u32 s1, s41, s3
	s_nop 0
	v_addc_co_u32_e32 v55, vcc, 0, v53, vcc
	flat_load_dword v63, v[54:55] offset:3584
	v_lshl_add_u64 v[54:55], s[40:41], 0, v[8:9]
	v_add_co_u32_e32 v56, vcc, 0xfc2a000, v54
	s_add_i32 s42, s42, s44
	s_nop 0
	v_addc_co_u32_e32 v57, vcc, 0, v55, vcc
	flat_load_ushort v64, v[56:57]
	v_mov_b32_e32 v57, s1
	s_add_u32 s2, s2, s50
	s_addc_u32 s3, s3, s51
	v_lshl_add_u64 v[4:5], v[4:5], 0, s[52:53]
	v_lshl_add_u64 v[8:9], v[8:9], 0, s[54:55]
	s_cmp_lt_i32 s42, 0x8100
	v_mov_b32_e32 v56, s0
	v_add_co_u32_e32 v56, vcc, 0x7984000, v56
	s_mov_b32 s0, 0xffff6000
	s_nop 0
	v_addc_co_u32_e32 v57, vcc, 0, v57, vcc
	v_add_co_u32_e32 v58, vcc, s96, v6
	flat_load_dword v65, v[56:57]
	flat_load_dword v66, v[56:57] offset:32
	flat_load_dword v67, v[56:57] offset:64
	flat_load_dword v68, v[56:57] offset:96
	flat_load_dword v69, v[56:57] offset:128
	flat_load_dword v70, v[56:57] offset:160
	v_addc_co_u32_e32 v59, vcc, -1, v7, vcc
	global_load_dword v71, v[58:59], off offset:-512
	v_add_co_u32_e32 v58, vcc, 0x256da000, v52
	s_nop 1
	v_addc_co_u32_e32 v59, vcc, 0, v53, vcc
	flat_load_dword v72, v[58:59] offset:3584
	v_add_co_u32_e32 v58, vcc, 0xfc2c000, v54
	s_nop 1
	v_addc_co_u32_e32 v59, vcc, 0, v55, vcc
	flat_load_ushort v73, v[58:59] offset:2816
	v_add_co_u32_e32 v58, vcc, 0xffff3000, v6
	v_addc_co_u32_e32 v59, vcc, -1, v7, vcc
	global_load_dword v74, v[58:59], off offset:-1792
	v_add_co_u32_e32 v58, vcc, 0x256dd000, v52
	s_nop 1
	v_addc_co_u32_e32 v59, vcc, 0, v53, vcc
	flat_load_dword v75, v[58:59] offset:3584
	v_add_co_u32_e32 v58, vcc, 0xfc2f000, v54
	s_nop 1
	v_addc_co_u32_e32 v59, vcc, 0, v55, vcc
	flat_load_ushort v76, v[58:59] offset:1536
	v_add_co_u32_e32 v58, vcc, s0, v6
	s_movk_i32 s0, 0x8000
	s_nop 0
	v_addc_co_u32_e32 v59, vcc, -1, v7, vcc
	global_load_dword v77, v[58:59], off offset:-3072
	v_add_co_u32_e32 v58, vcc, 0x256e0000, v52
	v_addc_co_u32_e32 v59, vcc, 0, v53, vcc
	flat_load_dword v78, v[58:59] offset:3584
	v_add_co_u32_e32 v58, vcc, 0xfc32000, v54
	s_nop 1
	v_addc_co_u32_e32 v59, vcc, 0, v55, vcc
	flat_load_ushort v79, v[58:59] offset:256
	v_add_co_u32_e32 v58, vcc, s0, v6
	s_movk_i32 s0, 0xe000
	s_nop 0
	v_addc_co_u32_e32 v59, vcc, -1, v7, vcc
	global_load_dword v80, v[58:59], off offset:-256
	v_add_co_u32_e32 v58, vcc, 0x256e3000, v52
	v_addc_co_u32_e32 v59, vcc, 0, v53, vcc
	flat_load_dword v81, v[58:59] offset:3584
	v_add_co_u32_e32 v58, vcc, 0xfc34000, v54
	s_nop 1
	v_addc_co_u32_e32 v59, vcc, 0, v55, vcc
	flat_load_ushort v82, v[58:59] offset:3072
	v_add_co_u32_e32 v58, vcc, 0xffffb000, v6
	v_addc_co_u32_e32 v59, vcc, -1, v7, vcc
	global_load_dword v83, v[58:59], off offset:-1536
	v_add_co_u32_e32 v58, vcc, 0x256e6000, v52
	s_nop 1
	v_addc_co_u32_e32 v59, vcc, 0, v53, vcc
	flat_load_dword v84, v[58:59] offset:3584
	v_add_co_u32_e32 v58, vcc, 0xfc37000, v54
	s_nop 1
	v_addc_co_u32_e32 v59, vcc, 0, v55, vcc
	flat_load_ushort v85, v[58:59] offset:1792
	v_add_co_u32_e32 v58, vcc, s0, v6
	v_addc_co_u32_e32 v59, vcc, -1, v7, vcc
	v_add_co_u32_e32 v60, vcc, 0x256e9000, v52
	global_load_dword v86, v[58:59], off offset:-2816
	s_nop 0
	v_addc_co_u32_e32 v61, vcc, 0, v53, vcc
	flat_load_dword v87, v[60:61] offset:3584
	v_add_co_u32_e32 v60, vcc, 0xfc3a000, v54
	s_nop 1
	v_addc_co_u32_e32 v61, vcc, 0, v55, vcc
	v_add_co_u32_e32 v52, vcc, 0x256ec000, v52
	flat_load_ushort v88, v[60:61] offset:512
	s_nop 0
	v_addc_co_u32_e32 v53, vcc, 0, v53, vcc
	flat_load_dword v89, v[56:57] offset:192
	global_load_dword v90, v[6:7], off
	flat_load_dword v91, v[52:53] offset:3584
	v_add_co_u32_e32 v52, vcc, 0xfc3c000, v54
	v_lshl_add_u64 v[6:7], v[6:7], 0, s[54:55]
	s_nop 0
	v_addc_co_u32_e32 v53, vcc, 0, v55, vcc
	flat_load_ushort v92, v[52:53] offset:3328
	flat_load_dword v93, v[56:57] offset:224
	s_cselect_b32 s98, 1, 0
; __device__ __forceinline__ float bf1(bf16 h) { return __uint_as_float(((unsigned)h) << 16); }
; __device__ __forceinline__ void phase_post(const Args& A, const Ctx& C0, int l, int nskip) {
;     ...
;     for (int row0 = (C.bid - nskip) * 8; row0 < M; row0 += (C.G - nskip) * 8) {
;         float o[8], v[8], gr[8], rk[8];
; #pragma unroll
;         for (int i = 0; i < 8; ++i) { const size_t row = (size_t)(row0 + i);
;             o[i] = ((const float*)(Ub + row * UPITCH_B + UXC_B))[c]; v[i] = SCN[row * 3072 + hd * 384 + 320 + C.lane];
;             gr[i] = bf1(U[row * DIN + C_GR + c]); rk[i] = RKB[row * 8 + hd]; }
.LBB0_1187:
	s_waitcnt vmcnt(0) lgkmcnt(0)
	v_mov_b32_e32 v43, v62
	v_mov_b32_e32 v44, v63
	v_mov_b32_e32 v45, v64
	v_mov_b32_e32 v46, v65
	v_mov_b32_e32 v42, v66
	v_mov_b32_e32 v38, v67
	v_mov_b32_e32 v34, v68
	v_mov_b32_e32 v30, v69
	v_mov_b32_e32 v24, v70
	v_mov_b32_e32 v40, v71
	v_mov_b32_e32 v41, v72
	v_mov_b32_e32 v39, v73
	v_mov_b32_e32 v36, v74
	v_mov_b32_e32 v37, v75
	v_mov_b32_e32 v35, v76
	v_mov_b32_e32 v32, v77
	v_mov_b32_e32 v33, v78
	v_mov_b32_e32 v31, v79
	v_mov_b32_e32 v28, v80
	v_mov_b32_e32 v29, v81
	v_mov_b32_e32 v27, v82
	v_mov_b32_e32 v22, v83
	v_mov_b32_e32 v23, v84
	v_mov_b32_e32 v21, v85
	v_mov_b32_e32 v18, v86
	v_mov_b32_e32 v19, v87
	v_mov_b32_e32 v17, v88
	v_mov_b32_e32 v20, v89
	v_mov_b32_e32 v25, v90
	v_mov_b32_e32 v26, v91
	v_mov_b32_e32 v10, v92
	v_mov_b32_e32 v13, v93
	s_mov_b32 s99, s98
	s_cmp_lg_u32 s98, 0
	s_cbranch_scc0 .Lmy_post_noL
	v_add_co_u32_e32 v52, vcc, 0xfffee000, v6
	s_add_u32 s0, s40, s2
	s_nop 0
	v_addc_co_u32_e32 v53, vcc, -1, v7, vcc
	global_load_dword v62, v[52:53], off offset:-3328
	v_lshl_add_u64 v[52:53], s[40:41], 0, v[4:5]
	v_add_co_u32_e32 v54, vcc, 0x256d7000, v52
	s_addc_u32 s1, s41, s3
	s_nop 0
	v_addc_co_u32_e32 v55, vcc, 0, v53, vcc
	flat_load_dword v63, v[54:55] offset:3584
	v_lshl_add_u64 v[54:55], s[40:41], 0, v[8:9]
	v_add_co_u32_e32 v56, vcc, 0xfc2a000, v54
	s_add_i32 s42, s42, s44
	s_nop 0
	v_addc_co_u32_e32 v57, vcc, 0, v55, vcc
	flat_load_ushort v64, v[56:57]
	v_mov_b32_e32 v57, s1
	s_add_u32 s2, s2, s50
	s_addc_u32 s3, s3, s51
	v_lshl_add_u64 v[4:5], v[4:5], 0, s[52:53]
	v_lshl_add_u64 v[8:9], v[8:9], 0, s[54:55]
	s_cmp_lt_i32 s42, 0x8100
	v_mov_b32_e32 v56, s0
	v_add_co_u32_e32 v56, vcc, 0x7984000, v56
	s_mov_b32 s0, 0xffff6000
	s_nop 0
	v_addc_co_u32_e32 v57, vcc, 0, v57, vcc
	v_add_co_u32_e32 v58, vcc, s96, v6
	flat_load_dword v65, v[56:57]
	flat_load_dword v66, v[56:57] offset:32
	flat_load_dword v67, v[56:57] offset:64
	flat_load_dword v68, v[56:57] offset:96
	flat_load_dword v69, v[56:57] offset:128
	flat_load_dword v70, v[56:57] offset:160
	v_addc_co_u32_e32 v59, vcc, -1, v7, vcc
	global_load_dword v71, v[58:59], off offset:-512
	v_add_co_u32_e32 v58, vcc, 0x256da000, v52
	s_nop 1
	v_addc_co_u32_e32 v59, vcc, 0, v53, vcc
	flat_load_dword v72, v[58:59] offset:3584
	v_add_co_u32_e32 v58, vcc, 0xfc2c000, v54
	s_nop 1
	v_addc_co_u32_e32 v59, vcc, 0, v55, vcc
	flat_load_ushort v73, v[58:59] offset:2816
	v_add_co_u32_e32 v58, vcc, 0xffff3000, v6
	v_addc_co_u32_e32 v59, vcc, -1, v7, vcc
	global_load_dword v74, v[58:59], off offset:-1792
	v_add_co_u32_e32 v58, vcc, 0x256dd000, v52
	s_nop 1
	v_addc_co_u32_e32 v59, vcc, 0, v53, vcc
	flat_load_dword v75, v[58:59] offset:3584
	v_add_co_u32_e32 v58, vcc, 0xfc2f000, v54
	s_nop 1
	v_addc_co_u32_e32 v59, vcc, 0, v55, vcc
	flat_load_ushort v76, v[58:59] offset:1536
	v_add_co_u32_e32 v58, vcc, s0, v6
	s_movk_i32 s0, 0x8000
	s_nop 0
	v_addc_co_u32_e32 v59, vcc, -1, v7, vcc
	global_load_dword v77, v[58:59], off offset:-3072
	v_add_co_u32_e32 v58, vcc, 0x256e0000, v52
	v_addc_co_u32_e32 v59, vcc, 0, v53, vcc
	flat_load_dword v78, v[58:59] offset:3584
	v_add_co_u32_e32 v58, vcc, 0xfc32000, v54
	s_nop 1
	v_addc_co_u32_e32 v59, vcc, 0, v55, vcc
	flat_load_ushort v79, v[58:59] offset:256
	v_add_co_u32_e32 v58, vcc, s0, v6
	s_movk_i32 s0, 0xe000
	s_nop 0
	v_addc_co_u32_e32 v59, vcc, -1, v7, vcc
	global_load_dword v80, v[58:59], off offset:-256
	v_add_co_u32_e32 v58, vcc, 0x256e3000, v52
	v_addc_co_u32_e32 v59, vcc, 0, v53, vcc
	flat_load_dword v81, v[58:59] offset:3584
	v_add_co_u32_e32 v58, vcc, 0xfc34000, v54
	s_nop 1
	v_addc_co_u32_e32 v59, vcc, 0, v55, vcc
	flat_load_ushort v82, v[58:59] offset:3072
	v_add_co_u32_e32 v58, vcc, 0xffffb000, v6
	v_addc_co_u32_e32 v59, vcc, -1, v7, vcc
	global_load_dword v83, v[58:59], off offset:-1536
	v_add_co_u32_e32 v58, vcc, 0x256e6000, v52
	s_nop 1
	v_addc_co_u32_e32 v59, vcc, 0, v53, vcc
	flat_load_dword v84, v[58:59] offset:3584
	v_add_co_u32_e32 v58, vcc, 0xfc37000, v54
	s_nop 1
	v_addc_co_u32_e32 v59, vcc, 0, v55, vcc
	flat_load_ushort v85, v[58:59] offset:1792
	v_add_co_u32_e32 v58, vcc, s0, v6
	v_addc_co_u32_e32 v59, vcc, -1, v7, vcc
	v_add_co_u32_e32 v60, vcc, 0x256e9000, v52
	global_load_dword v86, v[58:59], off offset:-2816
	s_nop 0
	v_addc_co_u32_e32 v61, vcc, 0, v53, vcc
	flat_load_dword v87, v[60:61] offset:3584
	v_add_co_u32_e32 v60, vcc, 0xfc3a000, v54
	s_nop 1
	v_addc_co_u32_e32 v61, vcc, 0, v55, vcc
	v_add_co_u32_e32 v52, vcc, 0x256ec000, v52
	flat_load_ushort v88, v[60:61] offset:512
	s_nop 0
	v_addc_co_u32_e32 v53, vcc, 0, v53, vcc
	flat_load_dword v89, v[56:57] offset:192
	global_load_dword v90, v[6:7], off
	flat_load_dword v91, v[52:53] offset:3584
	v_add_co_u32_e32 v52, vcc, 0xfc3c000, v54
	v_lshl_add_u64 v[6:7], v[6:7], 0, s[54:55]
	s_nop 0
	v_addc_co_u32_e32 v53, vcc, 0, v55, vcc
	flat_load_ushort v92, v[52:53] offset:3328
	flat_load_dword v93, v[56:57] offset:224
	s_cselect_b32 s98, 1, 0
; __device__ __forceinline__ unsigned f2bf(float f) { unsigned u = __builtin_bit_cast(unsigned, f); return (u + 0x7fffu + ((u >> 16) & 1u)) >> 16; }
; __device__ __forceinline__ float silu(float x) { return x / (1.f + __expf(-x)); }
; __device__ __forceinline__ void phase_post(const Args& A, const Ctx& C0, int l, int nskip) {
;     ...
; #pragma unroll
;         for (int i = 0; i < 8; ++i) { const size_t row = (size_t)(row0 + i);
;             const float mean = wave_sum_l(o[i], C.lane) * (1.f / 64.f); const float dd = o[i] - mean; const float var = wave_sum_l(dd * dd, C.lane) * (1.f / 64.f);
;             const float y = dd * (1.f / sqrtf(var + LNX_EPS)) * lw + lb + rk[i] * v[i];
;             MIX[row * D + 1536 + c] = (bf16)f2bf(y * silu(gr[i])); }
.Lmy_post_noL:
	v_lshlrev_b32_e32 v45, 16, v45
	v_lshlrev_b32_e32 v39, 16, v39
	v_lshlrev_b32_e32 v35, 16, v35
	v_lshlrev_b32_e32 v31, 16, v31
	v_lshlrev_b32_e32 v27, 16, v27
	v_lshlrev_b32_e32 v21, 16, v21
	v_lshlrev_b32_e32 v17, 16, v17
	v_lshlrev_b32_e32 v12, 16, v10
	v_add_f32_dpp v10, v43, v43 quad_perm:[1,0,3,2] row_mask:0xf bank_mask:0xf bound_ctrl:1
	s_nop 1
	v_add_f32_dpp v10, v10, v10 quad_perm:[2,3,0,1] row_mask:0xf bank_mask:0xf bound_ctrl:1
	s_nop 1
	v_add_f32_dpp v10, v10, v10 row_half_mirror row_mask:0xf bank_mask:0xf bound_ctrl:1
	s_nop 1
	v_add_f32_dpp v10, v10, v10 row_mirror row_mask:0xf bank_mask:0xf bound_ctrl:1
	s_nop 0
	v_readlane_b32 s1, v10, 16
	v_readlane_b32 s0, v10, 0
	s_nop 0
	v_mov_b32_e32 v11, s1
	v_readlane_b32 s1, v10, 48
	v_add_f32_e32 v11, s0, v11
	v_readlane_b32 s0, v10, 32
	v_mov_b32_e32 v10, s1
	s_nop 0
	v_add_f32_e32 v10, s0, v10
	v_add_f32_e32 v10, v11, v10
	v_fmac_f32_e32 v43, 0xbc800000, v10
	v_mul_f32_e32 v10, v43, v43
	s_nop 1
	v_mov_b32_dpp v10, v10 quad_perm:[1,0,3,2] row_mask:0xf bank_mask:0xf bound_ctrl:1
	v_fmac_f32_e32 v10, v43, v43
	s_nop 1
	v_add_f32_dpp v10, v10, v10 quad_perm:[2,3,0,1] row_mask:0xf bank_mask:0xf bound_ctrl:1
	s_nop 1
	v_add_f32_dpp v10, v10, v10 row_half_mirror row_mask:0xf bank_mask:0xf bound_ctrl:1
	s_nop 1
	v_add_f32_dpp v10, v10, v10 row_mirror row_mask:0xf bank_mask:0xf bound_ctrl:1
	s_nop 0
	v_readlane_b32 s1, v10, 16
	v_readlane_b32 s0, v10, 0
	s_nop 0
	v_mov_b32_e32 v11, s1
	v_readlane_b32 s1, v10, 48
	v_add_f32_e32 v11, s0, v11
	v_readlane_b32 s0, v10, 32
	v_mov_b32_e32 v10, s1
	s_nop 0
	v_add_f32_e32 v10, s0, v10
	v_add_f32_e32 v10, v11, v10
	v_fmamk_f32 v10, v10, 0x3c800000, v50
	v_cmp_gt_f32_e32 vcc, s7, v10
	v_mul_f32_e32 v11, 0x4f800000, v10
	s_nop 0
	v_cndmask_b32_e32 v10, v10, v11, vcc
	v_sqrt_f32_e32 v11, v10
	s_nop 0
	v_add_u32_e32 v14, -1, v11
	v_fma_f32 v15, -v14, v11, v10
	v_cmp_ge_f32_e64 s[0:1], 0, v15
	v_add_u32_e32 v15, 1, v11
	s_nop 0
	v_cndmask_b32_e64 v14, v11, v14, s[0:1]
	v_fma_f32 v11, -v15, v11, v10
	v_cmp_lt_f32_e64 s[0:1], 0, v11
	s_nop 1
	v_cndmask_b32_e64 v11, v14, v15, s[0:1]
	v_mul_f32_e32 v14, 0x37800000, v11
	v_cndmask_b32_e32 v11, v11, v14, vcc
	v_cmp_class_f32_e32 vcc, v10, v207
	s_nop 1
	v_cndmask_b32_e32 v10, v11, v10, vcc
	v_div_scale_f32 v11, s[0:1], v10, v10, 1.0
	v_rcp_f32_e32 v14, v11
	s_nop 0
	v_fma_f32 v15, -v11, v14, 1.0
	v_fmac_f32_e32 v14, v15, v14
	v_div_scale_f32 v15, vcc, 1.0, v10, 1.0
	v_mul_f32_e32 v47, v15, v14
	v_fma_f32 v48, -v11, v47, v15
	v_fmac_f32_e32 v47, v48, v14
	v_fma_f32 v11, -v11, v47, v15
	v_div_fmas_f32 v11, v11, v14, v47
	v_div_fixup_f32 v10, v11, v10, 1.0
	v_mul_f32_e32 v11, 0xbfb8aa3b, v45
	v_exp_f32_e32 v11, v11
	v_mul_f32_e32 v10, v43, v10
	v_fma_f32 v10, v0, v10, v16
	v_fmac_f32_e32 v10, v44, v46
	v_add_f32_e32 v11, 1.0, v11
	v_div_scale_f32 v14, s[0:1], v11, v11, v45
	v_rcp_f32_e32 v15, v14
	s_mov_b32 s0, 0x7b28000
	v_fma_f32 v43, -v14, v15, 1.0
	v_fmac_f32_e32 v15, v43, v15
	v_div_scale_f32 v43, vcc, v45, v11, v45
	v_mul_f32_e32 v44, v43, v15
	v_fma_f32 v46, -v14, v44, v43
	v_fmac_f32_e32 v44, v46, v15
	v_fma_f32 v14, -v14, v44, v43
	v_div_fmas_f32 v14, v14, v15, v44
	v_div_fixup_f32 v11, v14, v11, v45
	v_mul_f32_e32 v10, v11, v10
	v_bfe_u32 v11, v10, 16, 1
	v_add3_u32 v43, v10, v11, s33
	v_lshl_add_u64 v[10:11], s[40:41], 0, v[2:3]
	v_add_co_u32_e32 v14, vcc, s0, v10
	v_lshl_add_u64 v[2:3], v[2:3], 0, s[46:47]
	s_nop 0
	v_addc_co_u32_e32 v15, vcc, 0, v11, vcc
	flat_store_short_d16_hi v[14:15], v43 offset:1280
	v_add_f32_dpp v14, v40, v40 quad_perm:[1,0,3,2] row_mask:0xf bank_mask:0xf bound_ctrl:1
	s_nop 1
	v_add_f32_dpp v14, v14, v14 quad_perm:[2,3,0,1] row_mask:0xf bank_mask:0xf bound_ctrl:1
	s_nop 1
	v_add_f32_dpp v14, v14, v14 row_half_mirror row_mask:0xf bank_mask:0xf bound_ctrl:1
	s_nop 1
	v_add_f32_dpp v14, v14, v14 row_mirror row_mask:0xf bank_mask:0xf bound_ctrl:1
	s_nop 0
	v_readlane_b32 s1, v14, 16
	v_readlane_b32 s0, v14, 0
	s_nop 0
	v_mov_b32_e32 v15, s1
	v_readlane_b32 s1, v14, 48
	v_add_f32_e32 v15, s0, v15
	v_readlane_b32 s0, v14, 32
	v_mov_b32_e32 v14, s1
	s_nop 0
	v_add_f32_e32 v14, s0, v14
	v_add_f32_e32 v14, v15, v14
	v_fmac_f32_e32 v40, 0xbc800000, v14
	v_mul_f32_e32 v14, v40, v40
	s_nop 1
	v_mov_b32_dpp v14, v14 quad_perm:[1,0,3,2] row_mask:0xf bank_mask:0xf bound_ctrl:1
	v_fmac_f32_e32 v14, v40, v40
	s_nop 1
	v_add_f32_dpp v14, v14, v14 quad_perm:[2,3,0,1] row_mask:0xf bank_mask:0xf bound_ctrl:1
	s_nop 1
	v_add_f32_dpp v14, v14, v14 row_half_mirror row_mask:0xf bank_mask:0xf bound_ctrl:1
	s_nop 1
	v_add_f32_dpp v14, v14, v14 row_mirror row_mask:0xf bank_mask:0xf bound_ctrl:1
	s_nop 0
	v_readlane_b32 s1, v14, 16
	v_readlane_b32 s0, v14, 0
	s_nop 0
	v_mov_b32_e32 v15, s1
	v_readlane_b32 s1, v14, 48
	v_add_f32_e32 v15, s0, v15
	v_readlane_b32 s0, v14, 32
	v_mov_b32_e32 v14, s1
	s_nop 0
	v_add_f32_e32 v14, s0, v14
	v_add_f32_e32 v14, v15, v14
	v_fmamk_f32 v14, v14, 0x3c800000, v50
	v_cmp_gt_f32_e32 vcc, s7, v14
	v_mul_f32_e32 v15, 0x4f800000, v14
	s_nop 0
	v_cndmask_b32_e32 v14, v14, v15, vcc
	v_sqrt_f32_e32 v15, v14
	s_nop 0
	v_add_u32_e32 v43, -1, v15
	v_fma_f32 v44, -v43, v15, v14
	v_cmp_ge_f32_e64 s[0:1], 0, v44
	v_add_u32_e32 v44, 1, v15
	s_nop 0
	v_cndmask_b32_e64 v43, v15, v43, s[0:1]
	v_fma_f32 v15, -v44, v15, v14
	v_cmp_lt_f32_e64 s[0:1], 0, v15
	s_nop 1
	v_cndmask_b32_e64 v15, v43, v44, s[0:1]
	v_mul_f32_e32 v43, 0x37800000, v15
	v_cndmask_b32_e32 v15, v15, v43, vcc
	v_cmp_class_f32_e32 vcc, v14, v207
	s_nop 1
	v_cndmask_b32_e32 v14, v15, v14, vcc
	v_div_scale_f32 v15, s[0:1], v14, v14, 1.0
	v_rcp_f32_e32 v43, v15
	s_nop 0
	v_fma_f32 v44, -v15, v43, 1.0
; __device__ __forceinline__ unsigned f2bf(float f) { unsigned u = __builtin_bit_cast(unsigned, f); return (u + 0x7fffu + ((u >> 16) & 1u)) >> 16; }
; __device__ __forceinline__ float silu(float x) { return x / (1.f + __expf(-x)); }
; __device__ __forceinline__ void phase_post(const Args& A, const Ctx& C0, int l, int nskip) {
;     ...
; #pragma unroll
;         for (int i = 0; i < 8; ++i) { const size_t row = (size_t)(row0 + i);
;             const float mean = wave_sum_l(o[i], C.lane) * (1.f / 64.f); const float dd = o[i] - mean; const float var = wave_sum_l(dd * dd, C.lane) * (1.f / 64.f);
;             const float y = dd * (1.f / sqrtf(var + LNX_EPS)) * lw + lb + rk[i] * v[i];
;             MIX[row * D + 1536 + c] = (bf16)f2bf(y * silu(gr[i])); }
	v_fmac_f32_e32 v43, v44, v43
	v_div_scale_f32 v44, vcc, 1.0, v14, 1.0
	v_mul_f32_e32 v45, v44, v43
	v_fma_f32 v46, -v15, v45, v44
	v_fmac_f32_e32 v45, v46, v43
	v_fma_f32 v15, -v15, v45, v44
	v_div_fmas_f32 v15, v15, v43, v45
	v_div_fixup_f32 v14, v15, v14, 1.0
	v_mul_f32_e32 v15, 0xbfb8aa3b, v39
	v_exp_f32_e32 v15, v15
	v_mul_f32_e32 v14, v40, v14
	v_fma_f32 v14, v0, v14, v16
	v_fmac_f32_e32 v14, v41, v42
	v_add_f32_e32 v15, 1.0, v15
	v_div_scale_f32 v40, s[0:1], v15, v15, v39
	v_rcp_f32_e32 v41, v40
	s_mov_b32 s0, 0x7b29000
	v_fma_f32 v42, -v40, v41, 1.0
	v_fmac_f32_e32 v41, v42, v41
	v_div_scale_f32 v42, vcc, v39, v15, v39
	v_mul_f32_e32 v43, v42, v41
	v_fma_f32 v44, -v40, v43, v42
	v_fmac_f32_e32 v43, v44, v41
	v_fma_f32 v40, -v40, v43, v42
	v_div_fmas_f32 v40, v40, v41, v43
	v_div_fixup_f32 v15, v40, v15, v39
	v_mul_f32_e32 v14, v15, v14
	v_bfe_u32 v15, v14, 16, 1
	v_add3_u32 v39, v14, v15, s33
	v_add_co_u32_e32 v14, vcc, s0, v10
	s_nop 1
	v_addc_co_u32_e32 v15, vcc, 0, v11, vcc
	flat_store_short_d16_hi v[14:15], v39 offset:1280
	v_add_f32_dpp v14, v36, v36 quad_perm:[1,0,3,2] row_mask:0xf bank_mask:0xf bound_ctrl:1
	s_nop 1
	v_add_f32_dpp v14, v14, v14 quad_perm:[2,3,0,1] row_mask:0xf bank_mask:0xf bound_ctrl:1
	s_nop 1
	v_add_f32_dpp v14, v14, v14 row_half_mirror row_mask:0xf bank_mask:0xf bound_ctrl:1
	s_nop 1
	v_add_f32_dpp v14, v14, v14 row_mirror row_mask:0xf bank_mask:0xf bound_ctrl:1
	s_nop 0
	v_readlane_b32 s1, v14, 16
	v_readlane_b32 s0, v14, 0
	s_nop 0
	v_mov_b32_e32 v15, s1
	v_readlane_b32 s1, v14, 48
	v_add_f32_e32 v15, s0, v15
	v_readlane_b32 s0, v14, 32
	v_mov_b32_e32 v14, s1
	s_nop 0
	v_add_f32_e32 v14, s0, v14
	v_add_f32_e32 v14, v15, v14
	v_fmac_f32_e32 v36, 0xbc800000, v14
	v_mul_f32_e32 v14, v36, v36
	s_nop 1
	v_mov_b32_dpp v14, v14 quad_perm:[1,0,3,2] row_mask:0xf bank_mask:0xf bound_ctrl:1
	v_fmac_f32_e32 v14, v36, v36
	s_nop 1
	v_add_f32_dpp v14, v14, v14 quad_perm:[2,3,0,1] row_mask:0xf bank_mask:0xf bound_ctrl:1
	s_nop 1
	v_add_f32_dpp v14, v14, v14 row_half_mirror row_mask:0xf bank_mask:0xf bound_ctrl:1
	s_nop 1
	v_add_f32_dpp v14, v14, v14 row_mirror row_mask:0xf bank_mask:0xf bound_ctrl:1
	s_nop 0
	v_readlane_b32 s1, v14, 16
	v_readlane_b32 s0, v14, 0
	s_nop 0
	v_mov_b32_e32 v15, s1
	v_readlane_b32 s1, v14, 48
	v_add_f32_e32 v15, s0, v15
	v_readlane_b32 s0, v14, 32
	v_mov_b32_e32 v14, s1
	s_nop 0
	v_add_f32_e32 v14, s0, v14
	v_add_f32_e32 v14, v15, v14
	v_fmamk_f32 v14, v14, 0x3c800000, v50
	v_cmp_gt_f32_e32 vcc, s7, v14
	v_mul_f32_e32 v15, 0x4f800000, v14
	s_nop 0
	v_cndmask_b32_e32 v14, v14, v15, vcc
	v_sqrt_f32_e32 v15, v14
	s_nop 0
	v_add_u32_e32 v39, -1, v15
	v_fma_f32 v40, -v39, v15, v14
	v_cmp_ge_f32_e64 s[0:1], 0, v40
	v_add_u32_e32 v40, 1, v15
	s_nop 0
	v_cndmask_b32_e64 v39, v15, v39, s[0:1]
	v_fma_f32 v15, -v40, v15, v14
	v_cmp_lt_f32_e64 s[0:1], 0, v15
	s_nop 1
	v_cndmask_b32_e64 v15, v39, v40, s[0:1]
	v_mul_f32_e32 v39, 0x37800000, v15
	v_cndmask_b32_e32 v15, v15, v39, vcc
	v_cmp_class_f32_e32 vcc, v14, v207
	s_nop 1
	v_cndmask_b32_e32 v14, v15, v14, vcc
	v_div_scale_f32 v15, s[0:1], v14, v14, 1.0
	v_rcp_f32_e32 v39, v15
	s_nop 0
	v_fma_f32 v40, -v15, v39, 1.0
	v_fmac_f32_e32 v39, v40, v39
	v_div_scale_f32 v40, vcc, 1.0, v14, 1.0
	v_mul_f32_e32 v41, v40, v39
	v_fma_f32 v42, -v15, v41, v40
	v_fmac_f32_e32 v41, v42, v39
	v_fma_f32 v15, -v15, v41, v40
	v_div_fmas_f32 v15, v15, v39, v41
	v_div_fixup_f32 v14, v15, v14, 1.0
	v_mul_f32_e32 v15, 0xbfb8aa3b, v35
	v_exp_f32_e32 v15, v15
	v_mul_f32_e32 v14, v36, v14
	v_fma_f32 v14, v0, v14, v16
	v_fmac_f32_e32 v14, v37, v38
	v_add_f32_e32 v15, 1.0, v15
	v_div_scale_f32 v36, s[0:1], v15, v15, v35
	v_rcp_f32_e32 v37, v36
	s_mov_b32 s0, 0x7b2a000
	v_fma_f32 v38, -v36, v37, 1.0
	v_fmac_f32_e32 v37, v38, v37
	v_div_scale_f32 v38, vcc, v35, v15, v35
	v_mul_f32_e32 v39, v38, v37
	v_fma_f32 v40, -v36, v39, v38
	v_fmac_f32_e32 v39, v40, v37
	v_fma_f32 v36, -v36, v39, v38
	v_div_fmas_f32 v36, v36, v37, v39
	v_div_fixup_f32 v15, v36, v15, v35
	v_mul_f32_e32 v14, v15, v14
	v_bfe_u32 v15, v14, 16, 1
	v_add3_u32 v35, v14, v15, s33
	v_add_co_u32_e32 v14, vcc, s0, v10
	s_nop 1
	v_addc_co_u32_e32 v15, vcc, 0, v11, vcc
	flat_store_short_d16_hi v[14:15], v35 offset:1280
	v_add_f32_dpp v14, v32, v32 quad_perm:[1,0,3,2] row_mask:0xf bank_mask:0xf bound_ctrl:1
	s_nop 1
	v_add_f32_dpp v14, v14, v14 quad_perm:[2,3,0,1] row_mask:0xf bank_mask:0xf bound_ctrl:1
	s_nop 1
	v_add_f32_dpp v14, v14, v14 row_half_mirror row_mask:0xf bank_mask:0xf bound_ctrl:1
	s_nop 1
	v_add_f32_dpp v14, v14, v14 row_mirror row_mask:0xf bank_mask:0xf bound_ctrl:1
	s_nop 0
	v_readlane_b32 s1, v14, 16
	v_readlane_b32 s0, v14, 0
	s_nop 0
	v_mov_b32_e32 v15, s1
	v_readlane_b32 s1, v14, 48
	v_add_f32_e32 v15, s0, v15
	v_readlane_b32 s0, v14, 32
	v_mov_b32_e32 v14, s1
	s_nop 0
	v_add_f32_e32 v14, s0, v14
	v_add_f32_e32 v14, v15, v14
	v_fmac_f32_e32 v32, 0xbc800000, v14
	v_mul_f32_e32 v14, v32, v32
	s_nop 1
	v_mov_b32_dpp v14, v14 quad_perm:[1,0,3,2] row_mask:0xf bank_mask:0xf bound_ctrl:1
	v_fmac_f32_e32 v14, v32, v32
	s_nop 1
	v_add_f32_dpp v14, v14, v14 quad_perm:[2,3,0,1] row_mask:0xf bank_mask:0xf bound_ctrl:1
	s_nop 1
	v_add_f32_dpp v14, v14, v14 row_half_mirror row_mask:0xf bank_mask:0xf bound_ctrl:1
	s_nop 1
	v_add_f32_dpp v14, v14, v14 row_mirror row_mask:0xf bank_mask:0xf bound_ctrl:1
	s_nop 0
	v_readlane_b32 s1, v14, 16
	v_readlane_b32 s0, v14, 0
	s_nop 0
	v_mov_b32_e32 v15, s1
	v_readlane_b32 s1, v14, 48
	v_add_f32_e32 v15, s0, v15
	v_readlane_b32 s0, v14, 32
	v_mov_b32_e32 v14, s1
	s_nop 0
	v_add_f32_e32 v14, s0, v14
	v_add_f32_e32 v14, v15, v14
	v_fmamk_f32 v14, v14, 0x3c800000, v50
; __device__ __forceinline__ unsigned f2bf(float f) { unsigned u = __builtin_bit_cast(unsigned, f); return (u + 0x7fffu + ((u >> 16) & 1u)) >> 16; }
; __device__ __forceinline__ float silu(float x) { return x / (1.f + __expf(-x)); }
; __device__ __forceinline__ void phase_post(const Args& A, const Ctx& C0, int l, int nskip) {
;     ...
; #pragma unroll
;         for (int i = 0; i < 8; ++i) { const size_t row = (size_t)(row0 + i);
;             const float mean = wave_sum_l(o[i], C.lane) * (1.f / 64.f); const float dd = o[i] - mean; const float var = wave_sum_l(dd * dd, C.lane) * (1.f / 64.f);
;             const float y = dd * (1.f / sqrtf(var + LNX_EPS)) * lw + lb + rk[i] * v[i];
;             MIX[row * D + 1536 + c] = (bf16)f2bf(y * silu(gr[i])); }
	v_cmp_gt_f32_e32 vcc, s7, v14
	v_mul_f32_e32 v15, 0x4f800000, v14
	s_nop 0
	v_cndmask_b32_e32 v14, v14, v15, vcc
	v_sqrt_f32_e32 v15, v14
	s_nop 0
	v_add_u32_e32 v35, -1, v15
	v_fma_f32 v36, -v35, v15, v14
	v_cmp_ge_f32_e64 s[0:1], 0, v36
	v_add_u32_e32 v36, 1, v15
	s_nop 0
	v_cndmask_b32_e64 v35, v15, v35, s[0:1]
	v_fma_f32 v15, -v36, v15, v14
	v_cmp_lt_f32_e64 s[0:1], 0, v15
	s_nop 1
	v_cndmask_b32_e64 v15, v35, v36, s[0:1]
	v_mul_f32_e32 v35, 0x37800000, v15
	v_cndmask_b32_e32 v15, v15, v35, vcc
	v_cmp_class_f32_e32 vcc, v14, v207
	s_nop 1
	v_cndmask_b32_e32 v14, v15, v14, vcc
	v_div_scale_f32 v15, s[0:1], v14, v14, 1.0
	v_rcp_f32_e32 v35, v15
	s_nop 0
	v_fma_f32 v36, -v15, v35, 1.0
	v_fmac_f32_e32 v35, v36, v35
	v_div_scale_f32 v36, vcc, 1.0, v14, 1.0
	v_mul_f32_e32 v37, v36, v35
	v_fma_f32 v38, -v15, v37, v36
	v_fmac_f32_e32 v37, v38, v35
	v_fma_f32 v15, -v15, v37, v36
	v_div_fmas_f32 v15, v15, v35, v37
	v_div_fixup_f32 v14, v15, v14, 1.0
	v_mul_f32_e32 v15, 0xbfb8aa3b, v31
	v_exp_f32_e32 v15, v15
	v_mul_f32_e32 v14, v32, v14
	v_fma_f32 v14, v0, v14, v16
	v_fmac_f32_e32 v14, v33, v34
	v_add_f32_e32 v15, 1.0, v15
	v_div_scale_f32 v32, s[0:1], v15, v15, v31
	v_rcp_f32_e32 v33, v32
	s_mov_b32 s0, 0x7b2b000
	v_fma_f32 v34, -v32, v33, 1.0
	v_fmac_f32_e32 v33, v34, v33
	v_div_scale_f32 v34, vcc, v31, v15, v31
	v_mul_f32_e32 v35, v34, v33
	v_fma_f32 v36, -v32, v35, v34
	v_fmac_f32_e32 v35, v36, v33
	v_fma_f32 v32, -v32, v35, v34
	v_div_fmas_f32 v32, v32, v33, v35
	v_div_fixup_f32 v15, v32, v15, v31
	v_mul_f32_e32 v14, v15, v14
	v_bfe_u32 v15, v14, 16, 1
	v_add3_u32 v31, v14, v15, s33
	v_add_co_u32_e32 v14, vcc, s0, v10
	s_nop 1
	v_addc_co_u32_e32 v15, vcc, 0, v11, vcc
	flat_store_short_d16_hi v[14:15], v31 offset:1280
	v_add_f32_dpp v14, v28, v28 quad_perm:[1,0,3,2] row_mask:0xf bank_mask:0xf bound_ctrl:1
	s_nop 1
	v_add_f32_dpp v14, v14, v14 quad_perm:[2,3,0,1] row_mask:0xf bank_mask:0xf bound_ctrl:1
	s_nop 1
	v_add_f32_dpp v14, v14, v14 row_half_mirror row_mask:0xf bank_mask:0xf bound_ctrl:1
	s_nop 1
	v_add_f32_dpp v14, v14, v14 row_mirror row_mask:0xf bank_mask:0xf bound_ctrl:1
	s_nop 0
	v_readlane_b32 s1, v14, 16
	v_readlane_b32 s0, v14, 0
	s_nop 0
	v_mov_b32_e32 v15, s1
	v_readlane_b32 s1, v14, 48
	v_add_f32_e32 v15, s0, v15
	v_readlane_b32 s0, v14, 32
	v_mov_b32_e32 v14, s1
	s_nop 0
	v_add_f32_e32 v14, s0, v14
	v_add_f32_e32 v14, v15, v14
	v_fmac_f32_e32 v28, 0xbc800000, v14
	v_mul_f32_e32 v14, v28, v28
	s_nop 1
	v_mov_b32_dpp v14, v14 quad_perm:[1,0,3,2] row_mask:0xf bank_mask:0xf bound_ctrl:1
	v_fmac_f32_e32 v14, v28, v28
	s_nop 1
	v_add_f32_dpp v14, v14, v14 quad_perm:[2,3,0,1] row_mask:0xf bank_mask:0xf bound_ctrl:1
	s_nop 1
	v_add_f32_dpp v14, v14, v14 row_half_mirror row_mask:0xf bank_mask:0xf bound_ctrl:1
	s_nop 1
	v_add_f32_dpp v14, v14, v14 row_mirror row_mask:0xf bank_mask:0xf bound_ctrl:1
	s_nop 0
	v_readlane_b32 s1, v14, 16
	v_readlane_b32 s0, v14, 0
	s_nop 0
	v_mov_b32_e32 v15, s1
	v_readlane_b32 s1, v14, 48
	v_add_f32_e32 v15, s0, v15
	v_readlane_b32 s0, v14, 32
	v_mov_b32_e32 v14, s1
	s_nop 0
	v_add_f32_e32 v14, s0, v14
	v_add_f32_e32 v14, v15, v14
	v_fmamk_f32 v14, v14, 0x3c800000, v50
	v_cmp_gt_f32_e32 vcc, s7, v14
	v_mul_f32_e32 v15, 0x4f800000, v14
	s_nop 0
	v_cndmask_b32_e32 v14, v14, v15, vcc
	v_sqrt_f32_e32 v15, v14
	s_nop 0
	v_add_u32_e32 v31, -1, v15
	v_fma_f32 v32, -v31, v15, v14
	v_cmp_ge_f32_e64 s[0:1], 0, v32
	v_add_u32_e32 v32, 1, v15
	s_nop 0
	v_cndmask_b32_e64 v31, v15, v31, s[0:1]
	v_fma_f32 v15, -v32, v15, v14
	v_cmp_lt_f32_e64 s[0:1], 0, v15
	s_nop 1
	v_cndmask_b32_e64 v15, v31, v32, s[0:1]
	v_mul_f32_e32 v31, 0x37800000, v15
	v_cndmask_b32_e32 v15, v15, v31, vcc
	v_cmp_class_f32_e32 vcc, v14, v207
	s_nop 1
	v_cndmask_b32_e32 v14, v15, v14, vcc
	v_div_scale_f32 v15, s[0:1], v14, v14, 1.0
	v_rcp_f32_e32 v31, v15
	s_nop 0
	v_fma_f32 v32, -v15, v31, 1.0
	v_fmac_f32_e32 v31, v32, v31
	v_div_scale_f32 v32, vcc, 1.0, v14, 1.0
	v_mul_f32_e32 v33, v32, v31
	v_fma_f32 v34, -v15, v33, v32
	v_fmac_f32_e32 v33, v34, v31
	v_fma_f32 v15, -v15, v33, v32
	v_div_fmas_f32 v15, v15, v31, v33
	v_div_fixup_f32 v14, v15, v14, 1.0
	v_mul_f32_e32 v15, 0xbfb8aa3b, v27
	v_exp_f32_e32 v15, v15
	v_mul_f32_e32 v14, v28, v14
	v_fma_f32 v14, v0, v14, v16
	v_fmac_f32_e32 v14, v29, v30
	v_add_f32_e32 v15, 1.0, v15
	v_div_scale_f32 v28, s[0:1], v15, v15, v27
	v_rcp_f32_e32 v29, v28
	s_mov_b32 s0, 0x7b2c000
	v_fma_f32 v30, -v28, v29, 1.0
	v_fmac_f32_e32 v29, v30, v29
	v_div_scale_f32 v30, vcc, v27, v15, v27
	v_mul_f32_e32 v31, v30, v29
	v_fma_f32 v32, -v28, v31, v30
	v_fmac_f32_e32 v31, v32, v29
	v_fma_f32 v28, -v28, v31, v30
	v_div_fmas_f32 v28, v28, v29, v31
	v_div_fixup_f32 v15, v28, v15, v27
	v_mul_f32_e32 v14, v15, v14
	v_bfe_u32 v15, v14, 16, 1
	v_add3_u32 v27, v14, v15, s33
	v_add_co_u32_e32 v14, vcc, s0, v10
	s_nop 1
	v_addc_co_u32_e32 v15, vcc, 0, v11, vcc
	flat_store_short_d16_hi v[14:15], v27 offset:1280
	v_add_f32_dpp v14, v22, v22 quad_perm:[1,0,3,2] row_mask:0xf bank_mask:0xf bound_ctrl:1
	s_nop 1
	v_add_f32_dpp v14, v14, v14 quad_perm:[2,3,0,1] row_mask:0xf bank_mask:0xf bound_ctrl:1
	s_nop 1
	v_add_f32_dpp v14, v14, v14 row_half_mirror row_mask:0xf bank_mask:0xf bound_ctrl:1
	s_nop 1
	v_add_f32_dpp v14, v14, v14 row_mirror row_mask:0xf bank_mask:0xf bound_ctrl:1
	s_nop 0
	v_readlane_b32 s1, v14, 16
	v_readlane_b32 s0, v14, 0
	s_nop 0
	v_mov_b32_e32 v15, s1
	v_readlane_b32 s1, v14, 48
	v_add_f32_e32 v15, s0, v15
	v_readlane_b32 s0, v14, 32
	v_mov_b32_e32 v14, s1
	s_nop 0
	v_add_f32_e32 v14, s0, v14
	v_add_f32_e32 v14, v15, v14
	v_fmac_f32_e32 v22, 0xbc800000, v14
	v_mul_f32_e32 v14, v22, v22
	s_nop 1
; __device__ __forceinline__ unsigned f2bf(float f) { unsigned u = __builtin_bit_cast(unsigned, f); return (u + 0x7fffu + ((u >> 16) & 1u)) >> 16; }
; __device__ __forceinline__ float silu(float x) { return x / (1.f + __expf(-x)); }
; __device__ __forceinline__ void phase_post(const Args& A, const Ctx& C0, int l, int nskip) {
;     ...
; #pragma unroll
;         for (int i = 0; i < 8; ++i) { const size_t row = (size_t)(row0 + i);
;             const float mean = wave_sum_l(o[i], C.lane) * (1.f / 64.f); const float dd = o[i] - mean; const float var = wave_sum_l(dd * dd, C.lane) * (1.f / 64.f);
;             const float y = dd * (1.f / sqrtf(var + LNX_EPS)) * lw + lb + rk[i] * v[i];
;             MIX[row * D + 1536 + c] = (bf16)f2bf(y * silu(gr[i])); }
	v_mov_b32_dpp v14, v14 quad_perm:[1,0,3,2] row_mask:0xf bank_mask:0xf bound_ctrl:1
	v_fmac_f32_e32 v14, v22, v22
	s_nop 1
	v_add_f32_dpp v14, v14, v14 quad_perm:[2,3,0,1] row_mask:0xf bank_mask:0xf bound_ctrl:1
	s_nop 1
	v_add_f32_dpp v14, v14, v14 row_half_mirror row_mask:0xf bank_mask:0xf bound_ctrl:1
	s_nop 1
	v_add_f32_dpp v14, v14, v14 row_mirror row_mask:0xf bank_mask:0xf bound_ctrl:1
	s_nop 0
	v_readlane_b32 s1, v14, 16
	v_readlane_b32 s0, v14, 0
	s_nop 0
	v_mov_b32_e32 v15, s1
	v_readlane_b32 s1, v14, 48
	v_add_f32_e32 v15, s0, v15
	v_readlane_b32 s0, v14, 32
	v_mov_b32_e32 v14, s1
	s_nop 0
	v_add_f32_e32 v14, s0, v14
	v_add_f32_e32 v14, v15, v14
	v_fmamk_f32 v14, v14, 0x3c800000, v50
	v_cmp_gt_f32_e32 vcc, s7, v14
	v_mul_f32_e32 v15, 0x4f800000, v14
	s_nop 0
	v_cndmask_b32_e32 v14, v14, v15, vcc
	v_sqrt_f32_e32 v15, v14
	s_nop 0
	v_add_u32_e32 v27, -1, v15
	v_fma_f32 v28, -v27, v15, v14
	v_cmp_ge_f32_e64 s[0:1], 0, v28
	v_add_u32_e32 v28, 1, v15
	s_nop 0
	v_cndmask_b32_e64 v27, v15, v27, s[0:1]
	v_fma_f32 v15, -v28, v15, v14
	v_cmp_lt_f32_e64 s[0:1], 0, v15
	s_nop 1
	v_cndmask_b32_e64 v15, v27, v28, s[0:1]
	v_mul_f32_e32 v27, 0x37800000, v15
	v_cndmask_b32_e32 v15, v15, v27, vcc
	v_cmp_class_f32_e32 vcc, v14, v207
	s_nop 1
	v_cndmask_b32_e32 v14, v15, v14, vcc
	v_div_scale_f32 v15, s[0:1], v14, v14, 1.0
	v_rcp_f32_e32 v27, v15
	s_nop 0
	v_fma_f32 v28, -v15, v27, 1.0
	v_fmac_f32_e32 v27, v28, v27
	v_div_scale_f32 v28, vcc, 1.0, v14, 1.0
	v_mul_f32_e32 v29, v28, v27
	v_fma_f32 v30, -v15, v29, v28
	v_fmac_f32_e32 v29, v30, v27
	v_fma_f32 v15, -v15, v29, v28
	v_div_fmas_f32 v15, v15, v27, v29
	v_div_fixup_f32 v14, v15, v14, 1.0
	v_mul_f32_e32 v15, 0xbfb8aa3b, v21
	v_exp_f32_e32 v15, v15
	v_mul_f32_e32 v14, v22, v14
	v_fma_f32 v14, v0, v14, v16
	v_fmac_f32_e32 v14, v23, v24
	v_add_f32_e32 v15, 1.0, v15
	v_div_scale_f32 v22, s[0:1], v15, v15, v21
	v_rcp_f32_e32 v23, v22
	s_mov_b32 s0, 0x7b2d000
	v_fma_f32 v24, -v22, v23, 1.0
	v_fmac_f32_e32 v23, v24, v23
	v_div_scale_f32 v24, vcc, v21, v15, v21
	v_mul_f32_e32 v27, v24, v23
	v_fma_f32 v28, -v22, v27, v24
	v_fmac_f32_e32 v27, v28, v23
	v_fma_f32 v22, -v22, v27, v24
	v_div_fmas_f32 v22, v22, v23, v27
	v_div_fixup_f32 v15, v22, v15, v21
	v_mul_f32_e32 v14, v15, v14
	v_bfe_u32 v15, v14, 16, 1
	v_add3_u32 v21, v14, v15, s33
	v_add_co_u32_e32 v14, vcc, s0, v10
	s_nop 1
	v_addc_co_u32_e32 v15, vcc, 0, v11, vcc
	flat_store_short_d16_hi v[14:15], v21 offset:1280
	v_add_f32_dpp v14, v18, v18 quad_perm:[1,0,3,2] row_mask:0xf bank_mask:0xf bound_ctrl:1
	s_nop 1
	v_add_f32_dpp v14, v14, v14 quad_perm:[2,3,0,1] row_mask:0xf bank_mask:0xf bound_ctrl:1
	s_nop 1
	v_add_f32_dpp v14, v14, v14 row_half_mirror row_mask:0xf bank_mask:0xf bound_ctrl:1
	s_nop 1
	v_add_f32_dpp v14, v14, v14 row_mirror row_mask:0xf bank_mask:0xf bound_ctrl:1
	s_nop 0
	v_readlane_b32 s1, v14, 16
	v_readlane_b32 s0, v14, 0
	s_nop 0
	v_mov_b32_e32 v15, s1
	v_readlane_b32 s1, v14, 48
	v_add_f32_e32 v15, s0, v15
	v_readlane_b32 s0, v14, 32
	v_mov_b32_e32 v14, s1
	s_nop 0
	v_add_f32_e32 v14, s0, v14
	v_add_f32_e32 v14, v15, v14
	v_fmac_f32_e32 v18, 0xbc800000, v14
	v_mul_f32_e32 v14, v18, v18
	s_nop 1
	v_mov_b32_dpp v14, v14 quad_perm:[1,0,3,2] row_mask:0xf bank_mask:0xf bound_ctrl:1
	v_fmac_f32_e32 v14, v18, v18
	s_nop 1
	v_add_f32_dpp v14, v14, v14 quad_perm:[2,3,0,1] row_mask:0xf bank_mask:0xf bound_ctrl:1
	s_nop 1
	v_add_f32_dpp v14, v14, v14 row_half_mirror row_mask:0xf bank_mask:0xf bound_ctrl:1
	s_nop 1
	v_add_f32_dpp v14, v14, v14 row_mirror row_mask:0xf bank_mask:0xf bound_ctrl:1
	s_nop 0
	v_readlane_b32 s1, v14, 16
	v_readlane_b32 s0, v14, 0
	s_nop 0
	v_mov_b32_e32 v15, s1
	v_readlane_b32 s1, v14, 48
	v_add_f32_e32 v15, s0, v15
	v_readlane_b32 s0, v14, 32
	v_mov_b32_e32 v14, s1
	s_nop 0
	v_add_f32_e32 v14, s0, v14
	v_add_f32_e32 v14, v15, v14
	v_fmamk_f32 v14, v14, 0x3c800000, v50
	v_cmp_gt_f32_e32 vcc, s7, v14
	v_mul_f32_e32 v15, 0x4f800000, v14
	s_nop 0
	v_cndmask_b32_e32 v14, v14, v15, vcc
	v_sqrt_f32_e32 v15, v14
	s_nop 0
	v_add_u32_e32 v21, -1, v15
	v_fma_f32 v22, -v21, v15, v14
	v_cmp_ge_f32_e64 s[0:1], 0, v22
	v_add_u32_e32 v22, 1, v15
	s_nop 0
	v_cndmask_b32_e64 v21, v15, v21, s[0:1]
	v_fma_f32 v15, -v22, v15, v14
	v_cmp_lt_f32_e64 s[0:1], 0, v15
	s_nop 1
	v_cndmask_b32_e64 v15, v21, v22, s[0:1]
	v_mul_f32_e32 v21, 0x37800000, v15
	v_cndmask_b32_e32 v15, v15, v21, vcc
	v_cmp_class_f32_e32 vcc, v14, v207
	s_nop 1
; __device__ __forceinline__ unsigned f2bf(float f) { unsigned u = __builtin_bit_cast(unsigned, f); return (u + 0x7fffu + ((u >> 16) & 1u)) >> 16; }
; __device__ __forceinline__ float silu(float x) { return x / (1.f + __expf(-x)); }
; __device__ __forceinline__ void phase_post(const Args& A, const Ctx& C0, int l, int nskip) {
;     ...
; #pragma unroll
;         for (int i = 0; i < 8; ++i) { const size_t row = (size_t)(row0 + i);
;             const float mean = wave_sum_l(o[i], C.lane) * (1.f / 64.f); const float dd = o[i] - mean; const float var = wave_sum_l(dd * dd, C.lane) * (1.f / 64.f);
;             const float y = dd * (1.f / sqrtf(var + LNX_EPS)) * lw + lb + rk[i] * v[i];
;             MIX[row * D + 1536 + c] = (bf16)f2bf(y * silu(gr[i])); }
;     }
	v_cndmask_b32_e32 v14, v15, v14, vcc
	v_div_scale_f32 v15, s[0:1], v14, v14, 1.0
	v_rcp_f32_e32 v21, v15
	s_nop 0
	v_fma_f32 v22, -v15, v21, 1.0
	v_fmac_f32_e32 v21, v22, v21
	v_div_scale_f32 v22, vcc, 1.0, v14, 1.0
	v_mul_f32_e32 v23, v22, v21
	v_fma_f32 v24, -v15, v23, v22
	v_fmac_f32_e32 v23, v24, v21
	v_fma_f32 v15, -v15, v23, v22
	v_div_fmas_f32 v15, v15, v21, v23
	v_div_fixup_f32 v14, v15, v14, 1.0
	v_mul_f32_e32 v15, 0xbfb8aa3b, v17
	v_exp_f32_e32 v15, v15
	v_mul_f32_e32 v14, v18, v14
	v_fma_f32 v14, v0, v14, v16
	v_fmac_f32_e32 v14, v19, v20
	v_add_f32_e32 v15, 1.0, v15
	v_div_scale_f32 v18, s[0:1], v15, v15, v17
	v_rcp_f32_e32 v19, v18
	s_mov_b32 s0, 0x7b2e000
	v_fma_f32 v20, -v18, v19, 1.0
	v_fmac_f32_e32 v19, v20, v19
	v_div_scale_f32 v20, vcc, v17, v15, v17
	v_mul_f32_e32 v21, v20, v19
	v_fma_f32 v22, -v18, v21, v20
	v_fmac_f32_e32 v21, v22, v19
	v_fma_f32 v18, -v18, v21, v20
	v_div_fmas_f32 v18, v18, v19, v21
	v_div_fixup_f32 v15, v18, v15, v17
	v_mul_f32_e32 v14, v15, v14
	v_bfe_u32 v15, v14, 16, 1
	v_add3_u32 v17, v14, v15, s33
	v_add_co_u32_e32 v14, vcc, s0, v10
	s_nop 1
	v_addc_co_u32_e32 v15, vcc, 0, v11, vcc
	flat_store_short_d16_hi v[14:15], v17 offset:1280
	v_add_f32_dpp v14, v25, v25 quad_perm:[1,0,3,2] row_mask:0xf bank_mask:0xf bound_ctrl:1
	s_nop 1
	v_add_f32_dpp v14, v14, v14 quad_perm:[2,3,0,1] row_mask:0xf bank_mask:0xf bound_ctrl:1
	s_nop 1
	v_add_f32_dpp v14, v14, v14 row_half_mirror row_mask:0xf bank_mask:0xf bound_ctrl:1
	s_nop 1
	v_add_f32_dpp v14, v14, v14 row_mirror row_mask:0xf bank_mask:0xf bound_ctrl:1
	s_nop 0
	v_readlane_b32 s1, v14, 16
	v_readlane_b32 s0, v14, 0
	s_nop 0
	v_mov_b32_e32 v15, s1
	v_readlane_b32 s1, v14, 48
	v_add_f32_e32 v15, s0, v15
	v_readlane_b32 s0, v14, 32
	v_mov_b32_e32 v14, s1
	s_nop 0
	v_add_f32_e32 v14, s0, v14
	v_add_f32_e32 v14, v15, v14
	v_fmac_f32_e32 v25, 0xbc800000, v14
	v_mul_f32_e32 v14, v25, v25
	s_nop 1
	v_mov_b32_dpp v14, v14 quad_perm:[1,0,3,2] row_mask:0xf bank_mask:0xf bound_ctrl:1
	v_fmac_f32_e32 v14, v25, v25
	s_nop 1
	v_add_f32_dpp v14, v14, v14 quad_perm:[2,3,0,1] row_mask:0xf bank_mask:0xf bound_ctrl:1
	s_nop 1
	v_add_f32_dpp v14, v14, v14 row_half_mirror row_mask:0xf bank_mask:0xf bound_ctrl:1
	s_nop 1
	v_add_f32_dpp v14, v14, v14 row_mirror row_mask:0xf bank_mask:0xf bound_ctrl:1
	s_nop 0
	v_readlane_b32 s1, v14, 16
	v_readlane_b32 s0, v14, 0
	s_nop 0
	v_mov_b32_e32 v15, s1
	v_readlane_b32 s1, v14, 48
	v_add_f32_e32 v15, s0, v15
	v_readlane_b32 s0, v14, 32
	v_mov_b32_e32 v14, s1
	s_nop 0
	v_add_f32_e32 v14, s0, v14
	v_add_f32_e32 v14, v15, v14
	v_fmamk_f32 v14, v14, 0x3c800000, v50
	v_cmp_gt_f32_e32 vcc, s7, v14
	v_mul_f32_e32 v15, 0x4f800000, v14
	s_nop 0
	v_cndmask_b32_e32 v14, v14, v15, vcc
	v_sqrt_f32_e32 v15, v14
	s_nop 0
	v_add_u32_e32 v17, -1, v15
	v_fma_f32 v18, -v17, v15, v14
	v_cmp_ge_f32_e64 s[0:1], 0, v18
	v_add_u32_e32 v18, 1, v15
	s_nop 0
	v_cndmask_b32_e64 v17, v15, v17, s[0:1]
	v_fma_f32 v15, -v18, v15, v14
	v_cmp_lt_f32_e64 s[0:1], 0, v15
	s_nop 1
	v_cndmask_b32_e64 v15, v17, v18, s[0:1]
	v_mul_f32_e32 v17, 0x37800000, v15
	v_cndmask_b32_e32 v15, v15, v17, vcc
	v_cmp_class_f32_e32 vcc, v14, v207
	s_nop 1
	v_cndmask_b32_e32 v14, v15, v14, vcc
	v_div_scale_f32 v15, s[0:1], v14, v14, 1.0
	v_rcp_f32_e32 v17, v15
	s_nop 0
	v_fma_f32 v18, -v15, v17, 1.0
	v_fmac_f32_e32 v17, v18, v17
	v_div_scale_f32 v18, vcc, 1.0, v14, 1.0
	v_mul_f32_e32 v19, v18, v17
	v_fma_f32 v20, -v15, v19, v18
	v_fmac_f32_e32 v19, v20, v17
	v_fma_f32 v15, -v15, v19, v18
	v_div_fmas_f32 v15, v15, v17, v19
	v_div_fixup_f32 v14, v15, v14, 1.0
	v_mul_f32_e32 v14, v25, v14
	v_fma_f32 v14, v0, v14, v16
	v_fmac_f32_e32 v14, v26, v13
	v_mul_f32_e32 v13, 0xbfb8aa3b, v12
	v_exp_f32_e32 v13, v13
	s_nop 0
	v_add_f32_e32 v13, 1.0, v13
	v_div_scale_f32 v15, s[0:1], v13, v13, v12
	v_rcp_f32_e32 v17, v15
	s_mov_b32 s0, 0x7b2f000
	v_fma_f32 v18, -v15, v17, 1.0
	v_fmac_f32_e32 v17, v18, v17
	v_div_scale_f32 v18, vcc, v12, v13, v12
	v_mul_f32_e32 v19, v18, v17
	v_fma_f32 v20, -v15, v19, v18
	v_fmac_f32_e32 v19, v20, v17
	v_fma_f32 v15, -v15, v19, v18
	v_div_fmas_f32 v15, v15, v17, v19
	v_div_fixup_f32 v12, v15, v13, v12
	v_mul_f32_e32 v12, v12, v14
	v_bfe_u32 v13, v12, 16, 1
	v_add_co_u32_e32 v10, vcc, s0, v10
	v_add3_u32 v12, v12, v13, s33
	s_nop 0
	v_addc_co_u32_e32 v11, vcc, 0, v11, vcc
	flat_store_short_d16_hi v[10:11], v12 offset:1280
	s_cmp_lg_u32 s99, 0
	s_cbranch_scc1 .LBB0_1187
